# grid barrier: the globally last XCD leader releases all XCDs directly (adds to all per-XCC generation words); other leaders wait on their own XCC word - one fabric hop less per barrier
# speedup vs baseline: 1.0119x; 1.0032x over previous
.LBB0_317:
	s_or_b64 exec, exec, s[6:7]
	s_waitcnt vmcnt(0)
	v_readfirstlane_b32 s4, v2
	v_cvt_f32_u32_e32 v2, v0
	v_sub_u32_e32 v3, 0, v0
	v_add_u32_e32 v1, s4, v1
	s_add_u32 s4, s2, 0x3500
	v_rcp_iflag_f32_e32 v2, v2
	s_addc_u32 s5, s3, 0
	s_mov_b64 s[8:9], -1
	v_mul_f32_e32 v2, 0x4f7ffffe, v2
	v_cvt_u32_f32_e32 v2, v2
	v_mul_lo_u32 v3, v3, v2
	v_mul_hi_u32 v3, v2, v3
	v_add_u32_e32 v2, v2, v3
	v_mul_hi_u32 v2, v1, v2
	v_mul_lo_u32 v3, v2, v0
	v_sub_u32_e32 v3, v1, v3
	v_cmp_ge_u32_e32 vcc, v3, v0
	v_add_u32_e32 v4, 1, v2
	v_add_u32_e32 v1, 1, v1
	v_cndmask_b32_e32 v2, v2, v4, vcc
	v_sub_u32_e32 v4, v3, v0
	v_cndmask_b32_e32 v3, v3, v4, vcc
	v_cmp_ge_u32_e32 vcc, v3, v0
	v_add_u32_e32 v3, 1, v2
	s_nop 0
	v_cndmask_b32_e32 v2, v2, v3, vcc
	v_mul_lo_u32 v3, v0, v2
	v_add_u32_e32 v0, v3, v0
	v_cmp_ne_u32_e32 vcc, v1, v0
	v_mov_b64_e32 v[0:1], s[4:5]
	s_lshl_b32 s4, s30, 2
	s_add_u32 s4, s2, s4
	s_addc_u32 s5, s3, 0
	s_add_u32 s4, s4, 0x2400
	s_addc_u32 s5, s5, 0
	s_and_saveexec_b64 s[6:7], vcc
	s_cbranch_execnz .Lgs_poll_0
	s_mov_b64 exec, s[6:7]
	s_add_u32 s10, s2, 0x2400
	s_addc_u32 s11, s3, 0
	global_atomic_add v149, v211, s[10:11]
	global_atomic_add v149, v211, s[10:11] offset:256
	global_atomic_add v149, v211, s[10:11] offset:512
	global_atomic_add v149, v211, s[10:11] offset:768
	global_atomic_add v149, v211, s[10:11] offset:1024
	global_atomic_add v149, v211, s[10:11] offset:1280
	global_atomic_add v149, v211, s[10:11] offset:1536
	global_atomic_add v149, v211, s[10:11] offset:1792
	global_atomic_add v149, v211, s[10:11] offset:2048
	global_atomic_add v149, v211, s[10:11] offset:2304
	global_atomic_add v149, v211, s[10:11] offset:2560
	global_atomic_add v149, v211, s[10:11] offset:2816
	global_atomic_add v149, v211, s[10:11] offset:3072
	global_atomic_add v149, v211, s[10:11] offset:3328
	global_atomic_add v149, v211, s[10:11] offset:3584
	global_atomic_add v149, v211, s[10:11] offset:3840
	s_mov_b64 exec, 0
	s_branch .LBB0_329
.Lgs_poll_0:
	global_load_dword v0, v149, s[4:5] sc1
	s_mov_b64 s[18:19], 0
	s_waitcnt vmcnt(0)
	v_cmp_eq_u32_e32 vcc, v0, v2
	s_and_saveexec_b64 s[10:11], vcc
	s_cbranch_execz .LBB0_328
	s_add_u32 s8, s2, 0x200
	s_addc_u32 s9, s3, 0
	s_mov_b32 s31, 1
	s_branch .LBB0_321

.LBB0_331:
	s_or_b64 exec, exec, s[4:5]
	s_mov_b64 s[4:5], exec
	v_mbcnt_lo_u32_b32 v0, s4, 0
	v_mbcnt_hi_u32_b32 v0, s5, v0
	v_cmp_eq_u32_e32 vcc, 0, v0
	s_waitcnt vmcnt(0)
	buffer_inv sc1
	s_and_saveexec_b64 s[6:7], vcc
	s_cbranch_execz .LBB0_333
	s_add_i32 s48, s30, 0x900
	s_lshl_b64 s[8:9], s[48:49], 2
	s_add_u32 s2, s2, s8
	s_addc_u32 s3, s3, s9
	s_bcnt1_i32_b64 s4, s[4:5]
	v_mov_b32_e32 v0, s4
.LBB0_333:
	s_or_b64 exec, exec, s[6:7]
	s_waitcnt vmcnt(0)

.LBB0_562:
	s_or_b64 exec, exec, s[6:7]
	s_waitcnt vmcnt(0)
	v_readfirstlane_b32 s4, v2
	v_cvt_f32_u32_e32 v2, v0
	v_sub_u32_e32 v3, 0, v0
	v_add_u32_e32 v1, s4, v1
	s_add_u32 s4, s2, 0x3500
	v_rcp_iflag_f32_e32 v2, v2
	s_addc_u32 s5, s3, 0
	s_mov_b64 s[8:9], -1
	v_mul_f32_e32 v2, 0x4f7ffffe, v2
	v_cvt_u32_f32_e32 v2, v2
	v_mul_lo_u32 v3, v3, v2
	v_mul_hi_u32 v3, v2, v3
	v_add_u32_e32 v2, v2, v3
	v_mul_hi_u32 v2, v1, v2
	v_mul_lo_u32 v3, v2, v0
	v_sub_u32_e32 v3, v1, v3
	v_cmp_ge_u32_e32 vcc, v3, v0
	v_add_u32_e32 v4, 1, v2
	v_add_u32_e32 v1, 1, v1
	v_cndmask_b32_e32 v2, v2, v4, vcc
	v_sub_u32_e32 v4, v3, v0
	v_cndmask_b32_e32 v3, v3, v4, vcc
	v_cmp_ge_u32_e32 vcc, v3, v0
	v_add_u32_e32 v3, 1, v2
	s_nop 0
	v_cndmask_b32_e32 v2, v2, v3, vcc
	v_mul_lo_u32 v3, v0, v2
	v_add_u32_e32 v0, v3, v0
	v_cmp_ne_u32_e32 vcc, v1, v0
	v_mov_b64_e32 v[0:1], s[4:5]
	s_lshl_b32 s4, s22, 2
	s_add_u32 s4, s2, s4
	s_addc_u32 s5, s3, 0
	s_add_u32 s4, s4, 0x2400
	s_addc_u32 s5, s5, 0
	s_and_saveexec_b64 s[6:7], vcc
	s_cbranch_execnz .Lgs_poll_1
	s_mov_b64 exec, s[6:7]
	s_add_u32 s10, s2, 0x2400
	s_addc_u32 s11, s3, 0
	global_atomic_add v149, v211, s[10:11]
	global_atomic_add v149, v211, s[10:11] offset:256
	global_atomic_add v149, v211, s[10:11] offset:512
	global_atomic_add v149, v211, s[10:11] offset:768
	global_atomic_add v149, v211, s[10:11] offset:1024
	global_atomic_add v149, v211, s[10:11] offset:1280
	global_atomic_add v149, v211, s[10:11] offset:1536
	global_atomic_add v149, v211, s[10:11] offset:1792
	global_atomic_add v149, v211, s[10:11] offset:2048
	global_atomic_add v149, v211, s[10:11] offset:2304
	global_atomic_add v149, v211, s[10:11] offset:2560
	global_atomic_add v149, v211, s[10:11] offset:2816
	global_atomic_add v149, v211, s[10:11] offset:3072
	global_atomic_add v149, v211, s[10:11] offset:3328
	global_atomic_add v149, v211, s[10:11] offset:3584
	global_atomic_add v149, v211, s[10:11] offset:3840
	s_mov_b64 exec, 0
	s_branch .LBB0_574
.Lgs_poll_1:
	global_load_dword v0, v149, s[4:5] sc1
	s_mov_b64 s[12:13], 0
	s_waitcnt vmcnt(0)
	v_cmp_eq_u32_e32 vcc, v0, v2
	s_and_saveexec_b64 s[10:11], vcc
	s_cbranch_execz .LBB0_573
	s_add_u32 s8, s2, 0x200
	s_addc_u32 s9, s3, 0
	s_mov_b32 s23, 1
	s_branch .LBB0_566

.LBB0_576:
	s_or_b64 exec, exec, s[4:5]
	s_mov_b64 s[4:5], exec
	v_mbcnt_lo_u32_b32 v0, s4, 0
	v_mbcnt_hi_u32_b32 v0, s5, v0
	v_cmp_eq_u32_e32 vcc, 0, v0
	s_waitcnt vmcnt(0)
	buffer_inv sc1
	s_and_saveexec_b64 s[6:7], vcc
	s_cbranch_execz .LBB0_578
	s_add_i32 s48, s22, 0x900
	s_lshl_b64 s[8:9], s[48:49], 2
	s_add_u32 s2, s2, s8
	s_addc_u32 s3, s3, s9
	s_bcnt1_i32_b64 s4, s[4:5]
	v_mov_b32_e32 v0, s4
.LBB0_578:
	s_or_b64 exec, exec, s[6:7]
	s_waitcnt vmcnt(0)

.LBB0_815:
	s_or_b64 exec, exec, s[8:9]
	s_waitcnt vmcnt(0)
	v_readfirstlane_b32 s4, v2
	v_cvt_f32_u32_e32 v2, v0
	v_sub_u32_e32 v3, 0, v0
	v_add_u32_e32 v1, s4, v1
	s_add_u32 s4, s2, 0x3500
	v_rcp_iflag_f32_e32 v2, v2
	s_addc_u32 s5, s3, 0
	s_mov_b64 s[10:11], -1
	v_mul_f32_e32 v2, 0x4f7ffffe, v2
	v_cvt_u32_f32_e32 v2, v2
	v_mul_lo_u32 v3, v3, v2
	v_mul_hi_u32 v3, v2, v3
	v_add_u32_e32 v2, v2, v3
	v_mul_hi_u32 v2, v1, v2
	v_mul_lo_u32 v3, v2, v0
	v_sub_u32_e32 v3, v1, v3
	v_cmp_ge_u32_e32 vcc, v3, v0
	v_add_u32_e32 v4, 1, v2
	v_add_u32_e32 v1, 1, v1
	v_cndmask_b32_e32 v2, v2, v4, vcc
	v_sub_u32_e32 v4, v3, v0
	v_cndmask_b32_e32 v3, v3, v4, vcc
	v_cmp_ge_u32_e32 vcc, v3, v0
	v_add_u32_e32 v3, 1, v2
	s_nop 0
	v_cndmask_b32_e32 v2, v2, v3, vcc
	v_mul_lo_u32 v3, v0, v2
	v_add_u32_e32 v0, v3, v0
	v_cmp_ne_u32_e32 vcc, v1, v0
	v_mov_b64_e32 v[0:1], s[4:5]
	s_lshl_b32 s4, s24, 2
	s_add_u32 s4, s2, s4
	s_addc_u32 s5, s3, 0
	s_add_u32 s4, s4, 0x2400
	s_addc_u32 s5, s5, 0
	s_and_saveexec_b64 s[8:9], vcc
	s_cbranch_execnz .Lgs_poll_2
	s_mov_b64 exec, s[8:9]
	s_add_u32 s12, s2, 0x2400
	s_addc_u32 s13, s3, 0
	global_atomic_add v149, v211, s[12:13]
	global_atomic_add v149, v211, s[12:13] offset:256
	global_atomic_add v149, v211, s[12:13] offset:512
	global_atomic_add v149, v211, s[12:13] offset:768
	global_atomic_add v149, v211, s[12:13] offset:1024
	global_atomic_add v149, v211, s[12:13] offset:1280
	global_atomic_add v149, v211, s[12:13] offset:1536
	global_atomic_add v149, v211, s[12:13] offset:1792
	global_atomic_add v149, v211, s[12:13] offset:2048
	global_atomic_add v149, v211, s[12:13] offset:2304
	global_atomic_add v149, v211, s[12:13] offset:2560
	global_atomic_add v149, v211, s[12:13] offset:2816
	global_atomic_add v149, v211, s[12:13] offset:3072
	global_atomic_add v149, v211, s[12:13] offset:3328
	global_atomic_add v149, v211, s[12:13] offset:3584
	global_atomic_add v149, v211, s[12:13] offset:3840
	s_mov_b64 exec, 0
	s_branch .LBB0_827
.Lgs_poll_2:
	global_load_dword v0, v149, s[4:5] sc1
	s_mov_b64 s[14:15], 0
	s_waitcnt vmcnt(0)
	v_cmp_eq_u32_e32 vcc, v0, v2
	s_and_saveexec_b64 s[12:13], vcc
	s_cbranch_execz .LBB0_826
	s_add_u32 s10, s2, 0x200
	s_addc_u32 s11, s3, 0
	s_mov_b32 s25, 1
	s_branch .LBB0_819

.LBB0_829:
	s_or_b64 exec, exec, s[4:5]
	s_mov_b64 s[4:5], exec
	v_mbcnt_lo_u32_b32 v0, s4, 0
	v_mbcnt_hi_u32_b32 v0, s5, v0
	v_cmp_eq_u32_e32 vcc, 0, v0
	s_waitcnt vmcnt(0)
	buffer_inv sc1
	s_and_saveexec_b64 s[8:9], vcc
	s_cbranch_execz .LBB0_831
	s_add_i32 s48, s24, 0x900
	s_lshl_b64 s[10:11], s[48:49], 2
	s_add_u32 s2, s2, s10
	s_addc_u32 s3, s3, s11
	s_bcnt1_i32_b64 s4, s[4:5]
	v_mov_b32_e32 v0, s4
.LBB0_831:
	s_or_b64 exec, exec, s[8:9]
	s_waitcnt vmcnt(0)

.LBB0_944:
	s_or_b64 exec, exec, s[4:5]
	s_mov_b64 s[4:5], exec
	v_mbcnt_lo_u32_b32 v0, s4, 0
	v_mbcnt_hi_u32_b32 v0, s5, v0
	v_cmp_eq_u32_e32 vcc, 0, v0
	s_waitcnt vmcnt(0)
	buffer_inv sc1
	s_and_saveexec_b64 s[6:7], vcc
	s_cbranch_execz .LBB0_946
	s_add_i32 s48, s22, 0x900
	s_lshl_b64 s[8:9], s[48:49], 2
	s_add_u32 s2, s2, s8
	s_addc_u32 s3, s3, s9
	s_bcnt1_i32_b64 s4, s[4:5]
	v_mov_b32_e32 v0, s4
.LBB0_946:
	s_or_b64 exec, exec, s[6:7]
	s_waitcnt vmcnt(0)

.LBB0_1006:
	s_or_b64 exec, exec, s[4:5]
	s_mov_b64 s[4:5], exec
	v_mbcnt_lo_u32_b32 v0, s4, 0
	v_mbcnt_hi_u32_b32 v0, s5, v0
	v_cmp_eq_u32_e32 vcc, 0, v0
	s_waitcnt vmcnt(0)
	buffer_inv sc1
	s_and_saveexec_b64 s[6:7], vcc
	s_cbranch_execz .LBB0_1008
	s_add_i32 s48, s22, 0x900
	s_lshl_b64 s[8:9], s[48:49], 2
	s_add_u32 s2, s2, s8
	s_addc_u32 s3, s3, s9
	s_bcnt1_i32_b64 s4, s[4:5]
	v_mov_b32_e32 v0, s4
.LBB0_1008:
	s_or_b64 exec, exec, s[6:7]
	s_waitcnt vmcnt(0)

.LBB0_1316:
	s_or_b64 exec, exec, s[4:5]
	s_mov_b64 s[4:5], exec
	v_mbcnt_lo_u32_b32 v0, s4, 0
	v_mbcnt_hi_u32_b32 v0, s5, v0
	v_cmp_eq_u32_e32 vcc, 0, v0
	s_waitcnt vmcnt(0)
	buffer_inv sc1
	s_and_saveexec_b64 s[6:7], vcc
	s_cbranch_execz .LBB0_1318
	s_add_i32 s48, s22, 0x900
	s_lshl_b64 s[8:9], s[48:49], 2
	s_add_u32 s2, s2, s8
	s_addc_u32 s3, s3, s9
	s_bcnt1_i32_b64 s4, s[4:5]
	v_mov_b32_e32 v0, s4
.LBB0_1318:
	s_or_b64 exec, exec, s[6:7]
	s_waitcnt vmcnt(0)

.LBB0_1422:
	s_or_b64 exec, exec, s[4:5]
	s_mov_b64 s[4:5], exec
	v_mbcnt_lo_u32_b32 v0, s4, 0
	v_mbcnt_hi_u32_b32 v0, s5, v0
	v_cmp_eq_u32_e32 vcc, 0, v0
	s_waitcnt vmcnt(0)
	buffer_inv sc1
	s_and_saveexec_b64 s[6:7], vcc
	s_cbranch_execz .LBB0_1424
	s_add_i32 s48, s22, 0x900
	s_lshl_b64 s[8:9], s[48:49], 2
	s_add_u32 s2, s2, s8
	s_addc_u32 s3, s3, s9
	s_bcnt1_i32_b64 s4, s[4:5]
	v_mov_b32_e32 v0, s4
.LBB0_1424:
	s_or_b64 exec, exec, s[6:7]
	s_waitcnt vmcnt(0)

.LBB0_1511:
	s_add_i32 s48, s22, 0x900
	s_lshl_b64 s[8:9], s[48:49], 2
	s_add_u32 s2, s2, s8
	s_addc_u32 s3, s3, s9
	s_bcnt1_i32_b64 s4, s[4:5]
	v_mov_b32_e32 v0, s4
	s_getpc_b64 s[98:99]
